# attention: the half-wave row-sum exchange (ds_bpermute) issued before the g-loop's final barrier instead of at the head of the epilogue
# speedup vs baseline: 1.0106x; 1.0007x over previous
; __device__ __forceinline__ unsigned cvt_pk_bf16(float lo, float hi) { const f32x2 v = {lo, hi}; const bf16x2_t b = __builtin_convertvector(v, bf16x2_t); return __builtin_bit_cast(unsigned, b); }
; __device__ __forceinline__ void attn_phase(LAS unsigned char* lds, const bf16_t* Q, const bf16_t* Kb, const bf16_t* Vt, bf16_t* O, const float* relb, const float* qn, const float* kn, int vcu, int G) {
;     ...
;         const float lt = lrun + __shfl_xor(lrun, 32), il = 1.f / lt;
;         bf16_t* op = O + (rowbase + (size_t)qb * 256 + w * 32 + r32) * D + h * 64 + 4 * hi;
; #pragma unroll
;         for (int gq = 0; gq < 4; ++gq) {
;             u32x2 a; a.x = cvt_pk_bf16(o0[4 * gq] * il, o0[4 * gq + 1] * il); a.y = cvt_pk_bf16(o0[4 * gq + 2] * il, o0[4 * gq + 3] * il);
;             u32x2 c; c.x = cvt_pk_bf16(o1[4 * gq] * il, o1[4 * gq + 1] * il); c.y = cvt_pk_bf16(o1[4 * gq + 2] * il, o1[4 * gq + 3] * il);
;             *(u32x2*)(op + 8 * gq) = a; *(u32x2*)(op + 32 + 8 * gq) = c;
;         }
.LBB0_435:
	v_readlane_b32 s12, v252, 57
	v_readlane_b32 s13, v252, 58
	s_lshl_b32 s54, s35, 1
	v_mov_b32_e32 v135, v0
	s_waitcnt lgkmcnt(0)
	v_add_f32_e32 v1, v131, v1
	v_div_scale_f32 v4, s[18:19], v1, v1, 1.0
	v_rcp_f32_e32 v5, v4
	v_div_scale_f32 v6, vcc, 1.0, v1, 1.0
	v_lshl_add_u64 v[2:3], v[136:137], 1, s[12:13]
	v_fma_f32 v7, -v4, v5, 1.0
	v_fmac_f32_e32 v5, v7, v5
	v_mul_f32_e32 v7, v6, v5
	v_fma_f32 v8, -v4, v7, v6
	v_fmac_f32_e32 v7, v8, v5
	v_fma_f32 v4, -v4, v7, v6
	v_div_fmas_f32 v4, v4, v5, v7
	v_div_fixup_f32 v4, v4, v1, 1.0
	v_lshl_add_u64 v[2:3], v[2:3], 0, s[54:55]
	v_lshl_add_u64 v[2:3], v[2:3], 0, v[134:135]
	v_mbcnt_lo_u32_b32 v10, -1, 0
	v_lshrrev_b32_e32 v10, 5, v10
	v_lshlrev_b32_e32 v10, 3, v10
	v_mov_b32_e32 v11, 0
	v_lshl_add_u64 v[2:3], v[2:3], 0, v[10:11]
	v_pk_mul_f32 v[6:7], v[64:65], v[4:5] op_sel_hi:[1,0]
	v_pk_mul_f32 v[8:9], v[66:67], v[4:5] op_sel_hi:[1,0]
	v_cvt_pk_bf16_f32 v6, v6, v7
	v_cvt_pk_bf16_f32 v7, v8, v9
	v_pk_mul_f32 v[8:9], v[68:69], v[4:5] op_sel_hi:[1,0]
	v_pk_mul_f32 v[10:11], v[70:71], v[4:5] op_sel_hi:[1,0]
	v_cvt_pk_bf16_f32 v8, v8, v9
	v_cvt_pk_bf16_f32 v9, v10, v11
	s_nop 1
	v_permlane32_swap_b32_e32 v6, v8
	v_permlane32_swap_b32_e32 v7, v9
	global_store_dwordx4 v[2:3], v[6:9], off
	s_nop 1
	v_pk_mul_f32 v[6:7], v[72:73], v[4:5] op_sel_hi:[1,0]
	v_pk_mul_f32 v[8:9], v[74:75], v[4:5] op_sel_hi:[1,0]
	v_cvt_pk_bf16_f32 v6, v6, v7
	v_cvt_pk_bf16_f32 v7, v8, v9
	v_pk_mul_f32 v[8:9], v[76:77], v[4:5] op_sel_hi:[1,0]
	v_pk_mul_f32 v[10:11], v[78:79], v[4:5] op_sel_hi:[1,0]
	v_cvt_pk_bf16_f32 v8, v8, v9
	v_cvt_pk_bf16_f32 v9, v10, v11
	s_nop 1
	v_permlane32_swap_b32_e32 v6, v8
	v_permlane32_swap_b32_e32 v7, v9
	global_store_dwordx4 v[2:3], v[6:9], off offset:32
	s_nop 1
	v_pk_mul_f32 v[6:7], v[48:49], v[4:5] op_sel_hi:[1,0]
	v_pk_mul_f32 v[8:9], v[50:51], v[4:5] op_sel_hi:[1,0]
	v_cvt_pk_bf16_f32 v6, v6, v7
	v_cvt_pk_bf16_f32 v7, v8, v9
	v_pk_mul_f32 v[8:9], v[52:53], v[4:5] op_sel_hi:[1,0]
	v_pk_mul_f32 v[10:11], v[54:55], v[4:5] op_sel_hi:[1,0]
	v_cvt_pk_bf16_f32 v8, v8, v9
	v_cvt_pk_bf16_f32 v9, v10, v11
	s_nop 1
	v_permlane32_swap_b32_e32 v6, v8
	v_permlane32_swap_b32_e32 v7, v9
	global_store_dwordx4 v[2:3], v[6:9], off offset:64
	s_nop 1
	v_pk_mul_f32 v[6:7], v[56:57], v[4:5] op_sel_hi:[1,0]
	v_pk_mul_f32 v[8:9], v[58:59], v[4:5] op_sel_hi:[1,0]
	v_cvt_pk_bf16_f32 v6, v6, v7
	v_cvt_pk_bf16_f32 v7, v8, v9
	v_pk_mul_f32 v[8:9], v[60:61], v[4:5] op_sel_hi:[1,0]
	v_pk_mul_f32 v[10:11], v[62:63], v[4:5] op_sel_hi:[1,0]
	v_cvt_pk_bf16_f32 v8, v8, v9
	v_cvt_pk_bf16_f32 v9, v10, v11
	s_add_i32 s34, s34, s56
	s_add_i32 s30, s30, s56
	v_permlane32_swap_b32_e32 v6, v8
	v_permlane32_swap_b32_e32 v7, v9
	s_cmpk_lt_i32 s34, 0x800
	global_store_dwordx4 v[2:3], v[6:9], off offset:96
	s_cbranch_scc0 .LBB0_473

; #define ATT_BAR() do { asm volatile("s_waitcnt lgkmcnt(0)" ::: "memory"); __builtin_amdgcn_s_barrier(); asm volatile("" ::: "memory"); } while (0)
; __device__ __forceinline__ void attn_phase(LAS unsigned char* lds, const bf16_t* Q, const bf16_t* Kb, const bf16_t* Vt, bf16_t* O, const float* relb, const float* qn, const float* kn, int vcu, int G) {
;     ...
;         if (half == 0) ATT_BAR();
;         const float lt = lrun + __shfl_xor(lrun, 32), il = 1.f / lt;
.Lag_exit:
	s_waitcnt lgkmcnt(0)
	ds_bpermute_b32 v1, v147, v131
	s_barrier
